# speedup vs baseline: 1.0138x; 1.0138x over previous
.LBB0_387:
	s_ashr_i32 s0, s78, 31
	s_lshr_b32 s0, s0, 29
	s_add_i32 s0, s78, s0
	s_ashr_i32 s6, s0, 3
	s_and_b32 s0, s0, 0xfffff8
	s_sub_i32 s3, s78, s0
	s_ashr_i32 s7, s6, 31
	s_mul_i32 s11, s6, 0x2e00000
	s_mul_hi_i32 s10, s6, 0x2e00000
	s_add_u32 s0, s38, s11
	v_mov_b32_e32 v4, v228
	s_addc_u32 s1, s39, s10
	s_lshl_b32 s79, s3, 8
	v_mov_b64_e32 v[2:3], s[0:1]
	v_and_b32_e32 v6, 31, v4
	v_ashrrev_i32_e32 v5, 6, v4
	v_or_b32_e32 v0, s79, v6
	v_lshl_add_u32 v0, v5, 5, v0
	v_bfe_u32 v7, v4, 5, 1
	v_mad_i64_i32 v[2:3], s[8:9], v0, s48, v[2:3]
	v_lshl_add_u64 v[2:3], v[2:3], 0, s[14:15]
	v_lshlrev_b32_e32 v0, 4, v7
	v_lshl_add_u64 v[2:3], v[2:3], 0, v[0:1]
	v_readfirstlane_b32 s3, v5
	v_mov_b32_e32 v5, v228
	global_load_dwordx4 v[176:179], v[2:3], off
	global_load_dwordx4 v[180:183], v[2:3], off offset:32
	global_load_dwordx4 v[184:187], v[2:3], off offset:64
	global_load_dwordx4 v[188:191], v[2:3], off offset:96
	global_load_dwordx4 v[192:195], v[2:3], off offset:128
	global_load_dwordx4 v[196:199], v[2:3], off offset:160
	global_load_dwordx4 v[200:203], v[2:3], off offset:192
	global_load_dwordx4 v[204:207], v[2:3], off offset:224
	s_barrier
	s_add_u32 s0, s0, s14
	v_and_b32_e32 v3, 0x60, v5
	v_lshlrev_b32_e32 v9, 3, v5
	v_bfe_u32 v2, v5, 2, 2
	v_and_or_b32 v9, v9, 24, v3
	v_lshrrev_b32_e32 v3, 1, v5
	v_and_b32_e32 v8, 15, v5
	v_and_or_b32 v10, v3, 8, v2
	v_ashrrev_i32_e32 v3, 4, v5
	v_bitop3_b32 v2, v3, v8, 7 bitop3:0x6c
	v_mul_lo_u32 v11, v3, s48
	v_lshl_or_b32 v2, v2, 4, v11
	v_and_b32_e32 v11, 0x7ffff0, v3
	v_lshrrev_b32_e32 v3, 1, v3
	v_and_b32_e32 v3, 4, v3
	s_addc_u32 s1, s1, s15
	v_or3_b32 v3, v11, v3, v10
	s_add_u32 s8, s0, 0x1000
	v_mul_u32_u24_e32 v3, 0x2e00, v3
	s_addc_u32 s9, s1, 0
	s_lshl_b32 s24, s3, 10
	v_or_b32_e32 v3, v3, v9
	s_add_i32 s80, s24, 0
	v_lshlrev_b32_e32 v11, 1, v3
	v_mov_b32_e32 v3, v1
	s_add_i32 s81, s80, 0x10000
	v_lshl_add_u64 v[2:3], s[0:1], 0, v[2:3]
	v_lshl_add_u64 v[2:3], v[2:3], 0, s[16:17]
	s_mov_b32 m0, s81
	v_mov_b32_e32 v14, v1
	global_load_lds_dwordx4 v[2:3], off
	v_add_u32_e32 v2, 0x200, v5
	v_ashrrev_i32_e32 v3, 4, v2
	v_bitop3_b32 v2, v3, v8, 7 bitop3:0x6c
	v_mul_lo_u32 v5, v3, s48
	v_lshl_or_b32 v2, v2, 4, v5
	v_and_b32_e32 v5, 0x7ffff0, v3
	v_lshrrev_b32_e32 v3, 1, v3
	v_and_b32_e32 v3, 4, v3
	v_or3_b32 v3, v5, v3, v10
	v_mul_u32_u24_e32 v3, 0x2e00, v3
	v_or_b32_e32 v3, v3, v9
	v_lshlrev_b32_e32 v5, 1, v3
	v_mov_b32_e32 v3, v1
	s_mov_b32 m0, s80
	v_lshl_add_u64 v[2:3], s[0:1], 0, v[2:3]
	global_load_lds_dwordx4 v11, s[8:9]
	v_lshl_add_u64 v[2:3], v[2:3], 0, s[16:17]
	s_add_i32 m0, s80, 0x12000
	v_mov_b32_e32 v15, v1
	global_load_lds_dwordx4 v[2:3], off
	s_add_i32 m0, s80, 0x2000
	v_mov_b32_e32 v2, v228
	global_load_lds_dwordx4 v5, s[8:9]
	s_cmp_lg_u32 0, -1
	v_and_b32_e32 v8, 0x60, v2
	v_lshlrev_b32_e32 v9, 3, v2
	v_bfe_u32 v5, v2, 2, 2
	v_and_or_b32 v8, v9, 24, v8
	v_lshrrev_b32_e32 v9, 1, v2
	v_and_b32_e32 v3, 15, v2
	v_and_or_b32 v5, v9, 8, v5
	v_ashrrev_i32_e32 v9, 4, v2
	s_cselect_b32 s24, 0, 0
	v_bitop3_b32 v10, v9, v3, 7 bitop3:0x6c
	v_mul_lo_u32 v11, v9, s48
	s_add_i32 s27, s24, 0x10000
	v_lshl_or_b32 v10, v10, 4, v11
	v_and_b32_e32 v11, 0x7ffff0, v9
	v_lshrrev_b32_e32 v9, 1, v9
	s_add_u32 s8, s0, 0x170800
	v_and_b32_e32 v9, 4, v9
	s_addc_u32 s9, s1, 0
	v_or3_b32 v9, v11, v9, v5
	s_add_u32 s0, s0, 0x171000
	v_mul_u32_u24_e32 v9, 0x2e00, v9
	s_addc_u32 s1, s1, 0
	s_add_i32 m0, s80, 0x14000
	s_add_i32 s33, s80, 0x4000
	v_or_b32_e32 v9, v9, v8
	v_add_u32_e32 v2, 0x200, v2
	v_lshlrev_b32_e32 v9, 1, v9
	global_load_lds_dwordx4 v10, s[8:9]
	s_mov_b32 m0, s33
	v_ashrrev_i32_e32 v2, 4, v2
	global_load_lds_dwordx4 v9, s[0:1]
	v_bitop3_b32 v3, v2, v3, 7 bitop3:0x6c
	v_mul_lo_u32 v9, v2, s48
	v_lshl_or_b32 v3, v3, 4, v9
	v_and_b32_e32 v9, 0x7ffff0, v2
	v_lshrrev_b32_e32 v2, 1, v2
	v_and_b32_e32 v2, 4, v2
	v_or3_b32 v2, v9, v2, v5
	v_mul_u32_u24_e32 v2, 0x2e00, v2
	v_or_b32_e32 v2, v2, v8
	s_add_i32 m0, s80, 0x16000
	v_lshlrev_b32_e32 v2, 1, v2
	global_load_lds_dwordx4 v3, s[8:9]
	s_add_i32 m0, s80, 0x6000
	v_and_b32_e32 v3, 63, v4
	global_load_lds_dwordx4 v2, s[0:1]
	v_lshlrev_b32_e32 v8, 4, v4
	v_lshlrev_b32_e32 v5, 3, v3
	v_and_b32_e32 v8, 0xc0, v8
	v_lshlrev_b32_e32 v9, 1, v4
	v_and_b32_e32 v2, 0x3fffffc0, v4
	v_and_or_b32 v8, v5, 24, v8
	v_and_b32_e32 v9, 32, v9
	v_and_b32_e32 v5, 0x100, v5
	v_lshlrev_b32_e32 v5, 3, v5
	v_bitop3_b32 v4, v7, v4, 7 bitop3:0x78
	s_cmp_gt_i32 s3, 3
	v_lshl_add_u32 v2, v2, 2, s31
	v_or3_b32 v232, v8, v9, v5
	v_lshlrev_b32_e32 v5, 8, v6
	v_lshlrev_b32_e32 v4, 4, v4
	s_cselect_b64 s[34:35], 0, 0
	s_cmp_lt_i32 s3, 4
	v_add3_u32 v233, v5, s27, v4
	s_cselect_b64 s[46:47], -1, -1
	v_cmp_gt_u32_e64 s[8:9], 32, v3
	v_lshl_add_u32 v235, v6, 2, v2
	v_add_u32_e32 v236, v2, v0
	s_add_u32 s84, s25, s11
	v_mov_b32_e32 v0, v1
	v_mov_b32_e32 v2, v1
	v_mov_b32_e32 v3, v1
	v_mov_b32_e32 v4, v1
	v_mov_b32_e32 v5, v1
	v_mov_b32_e32 v6, v1
	v_mov_b32_e32 v7, v1
	v_mov_b32_e32 v8, v1
	v_mov_b32_e32 v9, v1
	v_mov_b32_e32 v10, v1
	v_mov_b32_e32 v11, v1
	v_mov_b32_e32 v12, v1
	v_mov_b32_e32 v13, v1
	v_mov_b64_e32 v[110:111], v[14:15]
	v_mov_b64_e32 v[94:95], v[14:15]
	v_mov_b64_e32 v[46:47], v[14:15]
	v_mov_b64_e32 v[30:31], v[14:15]
	v_mov_b64_e32 v[142:143], v[14:15]
	v_mov_b64_e32 v[126:127], v[14:15]
	v_mov_b64_e32 v[78:79], v[14:15]
	v_mov_b64_e32 v[62:63], v[14:15]
	v_add_u32_e32 v234, s24, v232
	s_addc_u32 s85, s30, s10
	s_mov_b64 s[56:57], 0
	s_xor_b64 s[76:77], s[34:35], -1
	s_mov_b32 s86, 0
	v_mov_b64_e32 v[108:109], v[12:13]
	v_mov_b64_e32 v[106:107], v[10:11]
	v_mov_b64_e32 v[104:105], v[8:9]
	v_mov_b64_e32 v[102:103], v[6:7]
	v_mov_b64_e32 v[100:101], v[4:5]
	v_mov_b64_e32 v[98:99], v[2:3]
	v_mov_b64_e32 v[96:97], v[0:1]
	v_mov_b64_e32 v[92:93], v[12:13]
	v_mov_b64_e32 v[90:91], v[10:11]
	v_mov_b64_e32 v[88:89], v[8:9]
	v_mov_b64_e32 v[86:87], v[6:7]
	v_mov_b64_e32 v[84:85], v[4:5]
	v_mov_b64_e32 v[82:83], v[2:3]
	v_mov_b64_e32 v[80:81], v[0:1]
	v_mov_b64_e32 v[44:45], v[12:13]
	v_mov_b64_e32 v[42:43], v[10:11]
	v_mov_b64_e32 v[40:41], v[8:9]
	v_mov_b64_e32 v[38:39], v[6:7]
	v_mov_b64_e32 v[36:37], v[4:5]
	v_mov_b64_e32 v[34:35], v[2:3]
	v_mov_b64_e32 v[32:33], v[0:1]
	v_mov_b64_e32 v[28:29], v[12:13]
	v_mov_b64_e32 v[26:27], v[10:11]
	v_mov_b64_e32 v[24:25], v[8:9]
	v_mov_b64_e32 v[22:23], v[6:7]
	v_mov_b64_e32 v[20:21], v[4:5]
	v_mov_b64_e32 v[18:19], v[2:3]
	v_mov_b64_e32 v[16:17], v[0:1]
	v_mov_b64_e32 v[140:141], v[12:13]
	v_mov_b64_e32 v[138:139], v[10:11]
	v_mov_b64_e32 v[136:137], v[8:9]
	v_mov_b64_e32 v[134:135], v[6:7]
	v_mov_b64_e32 v[132:133], v[4:5]
	v_mov_b64_e32 v[130:131], v[2:3]
	v_mov_b64_e32 v[128:129], v[0:1]
	v_mov_b64_e32 v[124:125], v[12:13]
	v_mov_b64_e32 v[122:123], v[10:11]
	v_mov_b64_e32 v[120:121], v[8:9]
	v_mov_b64_e32 v[118:119], v[6:7]
	v_mov_b64_e32 v[116:117], v[4:5]
	v_mov_b64_e32 v[114:115], v[2:3]
	v_mov_b64_e32 v[112:113], v[0:1]
	v_mov_b64_e32 v[76:77], v[12:13]
	v_mov_b64_e32 v[74:75], v[10:11]
	v_mov_b64_e32 v[72:73], v[8:9]
	v_mov_b64_e32 v[70:71], v[6:7]
	v_mov_b64_e32 v[68:69], v[4:5]
	v_mov_b64_e32 v[66:67], v[2:3]
	v_mov_b64_e32 v[64:65], v[0:1]
	v_mov_b64_e32 v[60:61], v[12:13]
	v_mov_b64_e32 v[58:59], v[10:11]
	v_mov_b64_e32 v[56:57], v[8:9]
	v_mov_b64_e32 v[54:55], v[6:7]
	v_mov_b64_e32 v[52:53], v[4:5]
	v_mov_b64_e32 v[50:51], v[2:3]
	v_mov_b64_e32 v[48:49], v[0:1]
	s_mov_b32 s87, 0
	v_mov_b32_e32 v237, v1
	v_mov_b32_e32 v238, v1
	v_mov_b32_e32 v208, v1
	v_mov_b32_e32 v209, v1
	v_mov_b32_e32 v210, v1
	v_mov_b32_e32 v211, v1
	v_lshrrev_b32_e32 v250, 4, v228
	v_and_b32_e32 v251, 15, v228
	v_and_b32_e32 v252, 7, v250
	v_xor_b32_e32 v251, v251, v252
	v_mul_u32_u24_e32 v250, 0x5c00, v250
	v_lshl_or_b32 v250, v251, 4, v250
	v_bfe_u32 v251, v228, 2, 2
	v_bfe_u32 v252, v228, 7, 1
	v_lshl_or_b32 v251, v252, 2, v251
	v_bfe_u32 v252, v228, 4, 1
	v_lshl_or_b32 v251, v252, 3, v251
	v_bfe_u32 v252, v228, 8, 1
	v_lshl_or_b32 v251, v252, 4, v251
	v_mul_u32_u24_e32 v251, 0x5c00, v251
	v_bfe_u32 v252, v228, 5, 2
	v_lshl_or_b32 v251, v252, 6, v251
	v_and_b32_e32 v252, 3, v228
	v_lshl_or_b32 v251, v252, 4, v251
	s_waitcnt vmcnt(0)
	s_branch .LBB0_389

.LBB0_1241:
	s_ashr_i32 s0, s42, 31
	s_lshr_b32 s0, s0, 26
	s_add_i32 s0, s42, s0
	s_ashr_i32 s6, s0, 6
	s_and_b32 s0, s0, 0xffffc0
	s_sub_i32 s3, s42, s0
	s_ashr_i32 s7, s6, 31
	s_mul_i32 s11, s6, 0x17000000
	s_mul_hi_i32 s10, s6, 0x17000000
	s_add_u32 s0, s38, s11
	v_mov_b32_e32 v4, v228
	s_addc_u32 s1, s39, s10
	s_lshl_b32 s56, s3, 8
	v_mov_b64_e32 v[2:3], s[0:1]
	v_and_b32_e32 v6, 31, v4
	v_ashrrev_i32_e32 v5, 6, v4
	v_or_b32_e32 v0, s56, v6
	v_lshl_add_u32 v0, v5, 5, v0
	v_bfe_u32 v7, v4, 5, 1
	v_mad_i64_i32 v[2:3], s[8:9], v0, s30, v[2:3]
	v_lshl_add_u64 v[2:3], v[2:3], 0, s[12:13]
	v_lshlrev_b32_e32 v0, 4, v7
	v_lshl_add_u64 v[2:3], v[2:3], 0, v[0:1]
	v_readfirstlane_b32 s3, v5
	v_mov_b32_e32 v5, v228
	global_load_dwordx4 v[176:179], v[2:3], off
	global_load_dwordx4 v[180:183], v[2:3], off offset:32
	global_load_dwordx4 v[184:187], v[2:3], off offset:64
	global_load_dwordx4 v[188:191], v[2:3], off offset:96
	global_load_dwordx4 v[192:195], v[2:3], off offset:128
	global_load_dwordx4 v[196:199], v[2:3], off offset:160
	global_load_dwordx4 v[200:203], v[2:3], off offset:192
	global_load_dwordx4 v[204:207], v[2:3], off offset:224
	s_barrier
	s_add_u32 s0, s0, s12
	v_and_b32_e32 v3, 0x60, v5
	v_lshlrev_b32_e32 v9, 3, v5
	v_bfe_u32 v2, v5, 2, 2
	v_and_or_b32 v9, v9, 24, v3
	v_lshrrev_b32_e32 v3, 1, v5
	v_and_b32_e32 v8, 15, v5
	v_and_or_b32 v10, v3, 8, v2
	v_ashrrev_i32_e32 v3, 4, v5
	v_bitop3_b32 v2, v3, v8, 7 bitop3:0x6c
	v_mul_lo_u32 v11, v3, s30
	v_lshl_or_b32 v2, v2, 4, v11
	v_and_b32_e32 v11, 0x7ffff0, v3
	v_lshrrev_b32_e32 v3, 1, v3
	v_and_b32_e32 v3, 4, v3
	s_addc_u32 s1, s1, s13
	v_or3_b32 v3, v11, v3, v10
	s_add_u32 s8, s0, 0x1000
	v_mul_u32_u24_e32 v3, 0x2e00, v3
	s_addc_u32 s9, s1, 0
	s_lshl_b32 s24, s3, 10
	v_or_b32_e32 v3, v3, v9
	s_add_i32 s57, s24, 0
	v_lshlrev_b32_e32 v11, 1, v3
	v_mov_b32_e32 v3, v1
	s_add_i32 s68, s57, 0x10000
	v_lshl_add_u64 v[2:3], s[0:1], 0, v[2:3]
	v_lshl_add_u64 v[2:3], v[2:3], 0, s[14:15]
	s_mov_b32 m0, s68
	v_mov_b32_e32 v14, v1
	global_load_lds_dwordx4 v[2:3], off
	v_add_u32_e32 v2, 0x200, v5
	v_ashrrev_i32_e32 v3, 4, v2
	v_bitop3_b32 v2, v3, v8, 7 bitop3:0x6c
	v_mul_lo_u32 v5, v3, s30
	v_lshl_or_b32 v2, v2, 4, v5
	v_and_b32_e32 v5, 0x7ffff0, v3
	v_lshrrev_b32_e32 v3, 1, v3
	v_and_b32_e32 v3, 4, v3
	v_or3_b32 v3, v5, v3, v10
	v_mul_u32_u24_e32 v3, 0x2e00, v3
	v_or_b32_e32 v3, v3, v9
	v_lshlrev_b32_e32 v5, 1, v3
	v_mov_b32_e32 v3, v1
	s_mov_b32 m0, s57
	v_lshl_add_u64 v[2:3], s[0:1], 0, v[2:3]
	global_load_lds_dwordx4 v11, s[8:9]
	v_lshl_add_u64 v[2:3], v[2:3], 0, s[14:15]
	s_add_i32 m0, s57, 0x12000
	v_mov_b32_e32 v15, v1
	global_load_lds_dwordx4 v[2:3], off
	s_add_i32 m0, s57, 0x2000
	v_mov_b32_e32 v2, v228
	global_load_lds_dwordx4 v5, s[8:9]
	s_cmp_lg_u32 0, -1
	v_and_b32_e32 v8, 0x60, v2
	v_lshlrev_b32_e32 v9, 3, v2
	v_bfe_u32 v5, v2, 2, 2
	v_and_or_b32 v8, v9, 24, v8
	v_lshrrev_b32_e32 v9, 1, v2
	v_and_b32_e32 v3, 15, v2
	v_and_or_b32 v5, v9, 8, v5
	v_ashrrev_i32_e32 v9, 4, v2
	s_cselect_b32 s24, 0, 0
	v_bitop3_b32 v10, v9, v3, 7 bitop3:0x6c
	v_mul_lo_u32 v11, v9, s30
	s_add_i32 s27, s24, 0x10000
	v_lshl_or_b32 v10, v10, 4, v11
	v_and_b32_e32 v11, 0x7ffff0, v9
	v_lshrrev_b32_e32 v9, 1, v9
	s_add_u32 s8, s0, 0x170800
	v_and_b32_e32 v9, 4, v9
	s_addc_u32 s9, s1, 0
	v_or3_b32 v9, v11, v9, v5
	s_add_u32 s0, s0, 0x171000
	v_mul_u32_u24_e32 v9, 0x2e00, v9
	s_addc_u32 s1, s1, 0
	s_add_i32 m0, s57, 0x14000
	s_add_i32 s33, s57, 0x4000
	v_or_b32_e32 v9, v9, v8
	v_add_u32_e32 v2, 0x200, v2
	v_lshlrev_b32_e32 v9, 1, v9
	global_load_lds_dwordx4 v10, s[8:9]
	s_mov_b32 m0, s33
	v_ashrrev_i32_e32 v2, 4, v2
	global_load_lds_dwordx4 v9, s[0:1]
	v_bitop3_b32 v3, v2, v3, 7 bitop3:0x6c
	v_mul_lo_u32 v9, v2, s30
	v_lshl_or_b32 v3, v3, 4, v9
	v_and_b32_e32 v9, 0x7ffff0, v2
	v_lshrrev_b32_e32 v2, 1, v2
	v_and_b32_e32 v2, 4, v2
	v_or3_b32 v2, v9, v2, v5
	v_mul_u32_u24_e32 v2, 0x2e00, v2
	v_or_b32_e32 v2, v2, v8
	s_add_i32 m0, s57, 0x16000
	v_lshlrev_b32_e32 v2, 1, v2
	global_load_lds_dwordx4 v3, s[8:9]
	s_add_i32 m0, s57, 0x6000
	v_and_b32_e32 v3, 63, v4
	global_load_lds_dwordx4 v2, s[0:1]
	v_lshlrev_b32_e32 v8, 4, v4
	v_lshlrev_b32_e32 v5, 3, v3
	v_and_b32_e32 v8, 0xc0, v8
	v_lshlrev_b32_e32 v9, 1, v4
	v_and_b32_e32 v2, 0x3fffffc0, v4
	v_and_or_b32 v8, v5, 24, v8
	v_and_b32_e32 v9, 32, v9
	v_and_b32_e32 v5, 0x100, v5
	v_lshlrev_b32_e32 v5, 3, v5
	v_bitop3_b32 v4, v7, v4, 7 bitop3:0x78
	s_cmp_gt_i32 s3, 3
	v_lshl_add_u32 v2, v2, 2, s25
	v_or3_b32 v232, v8, v9, v5
	v_lshlrev_b32_e32 v5, 8, v6
	v_lshlrev_b32_e32 v4, 4, v4
	s_cselect_b64 s[34:35], 0, 0
	s_cmp_lt_i32 s3, 4
	v_add3_u32 v233, v5, s27, v4
	s_cselect_b64 s[84:85], -1, -1
	v_cmp_gt_u32_e64 s[8:9], 32, v3
	v_lshl_add_u32 v235, v6, 2, v2
	v_add_u32_e32 v236, v2, v0
	s_add_u32 s69, s18, s11
	v_mov_b32_e32 v0, v1
	v_mov_b32_e32 v2, v1
	v_mov_b32_e32 v3, v1
	v_mov_b32_e32 v4, v1
	v_mov_b32_e32 v5, v1
	v_mov_b32_e32 v6, v1
	v_mov_b32_e32 v7, v1
	v_mov_b32_e32 v8, v1
	v_mov_b32_e32 v9, v1
	v_mov_b32_e32 v10, v1
	v_mov_b32_e32 v11, v1
	v_mov_b32_e32 v12, v1
	v_mov_b32_e32 v13, v1
	v_mov_b64_e32 v[110:111], v[14:15]
	v_mov_b64_e32 v[94:95], v[14:15]
	v_mov_b64_e32 v[62:63], v[14:15]
	v_mov_b64_e32 v[30:31], v[14:15]
	v_mov_b64_e32 v[142:143], v[14:15]
	v_mov_b64_e32 v[126:127], v[14:15]
	v_mov_b64_e32 v[78:79], v[14:15]
	v_mov_b64_e32 v[46:47], v[14:15]
	v_add_u32_e32 v234, s24, v232
	s_addc_u32 s76, s19, s10
	s_mov_b64 s[86:87], 0
	s_xor_b64 s[88:89], s[34:35], -1
	s_mov_b32 s77, 0
	v_mov_b64_e32 v[108:109], v[12:13]
	v_mov_b64_e32 v[106:107], v[10:11]
	v_mov_b64_e32 v[104:105], v[8:9]
	v_mov_b64_e32 v[102:103], v[6:7]
	v_mov_b64_e32 v[100:101], v[4:5]
	v_mov_b64_e32 v[98:99], v[2:3]
	v_mov_b64_e32 v[96:97], v[0:1]
	v_mov_b64_e32 v[92:93], v[12:13]
	v_mov_b64_e32 v[90:91], v[10:11]
	v_mov_b64_e32 v[88:89], v[8:9]
	v_mov_b64_e32 v[86:87], v[6:7]
	v_mov_b64_e32 v[84:85], v[4:5]
	v_mov_b64_e32 v[82:83], v[2:3]
	v_mov_b64_e32 v[80:81], v[0:1]
	v_mov_b64_e32 v[60:61], v[12:13]
	v_mov_b64_e32 v[58:59], v[10:11]
	v_mov_b64_e32 v[56:57], v[8:9]
	v_mov_b64_e32 v[54:55], v[6:7]
	v_mov_b64_e32 v[52:53], v[4:5]
	v_mov_b64_e32 v[50:51], v[2:3]
	v_mov_b64_e32 v[48:49], v[0:1]
	v_mov_b64_e32 v[28:29], v[12:13]
	v_mov_b64_e32 v[26:27], v[10:11]
	v_mov_b64_e32 v[24:25], v[8:9]
	v_mov_b64_e32 v[22:23], v[6:7]
	v_mov_b64_e32 v[20:21], v[4:5]
	v_mov_b64_e32 v[18:19], v[2:3]
	v_mov_b64_e32 v[16:17], v[0:1]
	v_mov_b64_e32 v[140:141], v[12:13]
	v_mov_b64_e32 v[138:139], v[10:11]
	v_mov_b64_e32 v[136:137], v[8:9]
	v_mov_b64_e32 v[134:135], v[6:7]
	v_mov_b64_e32 v[132:133], v[4:5]
	v_mov_b64_e32 v[130:131], v[2:3]
	v_mov_b64_e32 v[128:129], v[0:1]
	v_mov_b64_e32 v[124:125], v[12:13]
	v_mov_b64_e32 v[122:123], v[10:11]
	v_mov_b64_e32 v[120:121], v[8:9]
	v_mov_b64_e32 v[118:119], v[6:7]
	v_mov_b64_e32 v[116:117], v[4:5]
	v_mov_b64_e32 v[114:115], v[2:3]
	v_mov_b64_e32 v[112:113], v[0:1]
	v_mov_b64_e32 v[76:77], v[12:13]
	v_mov_b64_e32 v[74:75], v[10:11]
	v_mov_b64_e32 v[72:73], v[8:9]
	v_mov_b64_e32 v[70:71], v[6:7]
	v_mov_b64_e32 v[68:69], v[4:5]
	v_mov_b64_e32 v[66:67], v[2:3]
	v_mov_b64_e32 v[64:65], v[0:1]
	v_mov_b64_e32 v[44:45], v[12:13]
	v_mov_b64_e32 v[42:43], v[10:11]
	v_mov_b64_e32 v[40:41], v[8:9]
	v_mov_b64_e32 v[38:39], v[6:7]
	v_mov_b64_e32 v[36:37], v[4:5]
	v_mov_b64_e32 v[34:35], v[2:3]
	v_mov_b64_e32 v[32:33], v[0:1]
	s_mov_b32 s79, 0
	v_mov_b32_e32 v237, v1
	v_mov_b32_e32 v238, v1
	v_mov_b32_e32 v208, v1
	v_mov_b32_e32 v209, v1
	v_mov_b32_e32 v210, v1
	v_mov_b32_e32 v211, v1
	v_lshrrev_b32_e32 v250, 4, v228
	v_and_b32_e32 v251, 15, v228
	v_and_b32_e32 v252, 7, v250
	v_xor_b32_e32 v251, v251, v252
	v_mul_u32_u24_e32 v250, 0x5c00, v250
	v_lshl_or_b32 v250, v251, 4, v250
	v_bfe_u32 v251, v228, 2, 2
	v_bfe_u32 v252, v228, 7, 1
	v_lshl_or_b32 v251, v252, 2, v251
	v_bfe_u32 v252, v228, 4, 1
	v_lshl_or_b32 v251, v252, 3, v251
	v_bfe_u32 v252, v228, 8, 1
	v_lshl_or_b32 v251, v252, 4, v251
	v_mul_u32_u24_e32 v251, 0x5c00, v251
	v_bfe_u32 v252, v228, 5, 2
	v_lshl_or_b32 v251, v252, 6, v251
	v_and_b32_e32 v252, 3, v228
	v_lshl_or_b32 v251, v252, 4, v251
	s_waitcnt vmcnt(0)
	s_branch .LBB0_1243

.LBB0_2095:
	s_ashr_i32 s0, s62, 31
	s_lshr_b32 s0, s0, 26
	s_add_i32 s0, s62, s0
	s_ashr_i32 s34, s0, 6
	s_and_b32 s0, s0, 0xffffc0
	s_sub_i32 s3, s62, s0
	s_ashr_i32 s35, s34, 31
	s_mul_i32 s7, s34, 0x17000000
	s_mul_hi_i32 s6, s34, 0x17000000
	s_add_u32 s0, s38, s7
	v_mov_b32_e32 v4, v228
	s_addc_u32 s1, s39, s6
	s_lshl_b32 s63, s3, 8
	v_mov_b64_e32 v[2:3], s[0:1]
	v_and_b32_e32 v6, 31, v4
	v_ashrrev_i32_e32 v5, 6, v4
	v_or_b32_e32 v0, s63, v6
	v_lshl_add_u32 v0, v5, 5, v0
	v_bfe_u32 v7, v4, 5, 1
	v_mad_i64_i32 v[2:3], s[4:5], v0, s19, v[2:3]
	v_lshl_add_u64 v[2:3], v[2:3], 0, s[10:11]
	v_lshlrev_b32_e32 v0, 4, v7
	v_lshl_add_u64 v[2:3], v[2:3], 0, v[0:1]
	v_readfirstlane_b32 s3, v5
	v_mov_b32_e32 v5, v228
	global_load_dwordx4 v[176:179], v[2:3], off
	global_load_dwordx4 v[180:183], v[2:3], off offset:32
	global_load_dwordx4 v[184:187], v[2:3], off offset:64
	global_load_dwordx4 v[188:191], v[2:3], off offset:96
	global_load_dwordx4 v[192:195], v[2:3], off offset:128
	global_load_dwordx4 v[196:199], v[2:3], off offset:160
	global_load_dwordx4 v[200:203], v[2:3], off offset:192
	global_load_dwordx4 v[204:207], v[2:3], off offset:224
	s_barrier
	s_add_u32 s0, s0, s10
	v_and_b32_e32 v3, 0x60, v5
	v_lshlrev_b32_e32 v9, 3, v5
	v_bfe_u32 v2, v5, 2, 2
	v_and_or_b32 v9, v9, 24, v3
	v_lshrrev_b32_e32 v3, 1, v5
	v_and_b32_e32 v8, 15, v5
	v_and_or_b32 v10, v3, 8, v2
	v_ashrrev_i32_e32 v3, 4, v5
	v_bitop3_b32 v2, v3, v8, 7 bitop3:0x6c
	v_mul_lo_u32 v11, v3, s19
	v_lshl_or_b32 v2, v2, 4, v11
	v_and_b32_e32 v11, 0x7ffff0, v3
	v_lshrrev_b32_e32 v3, 1, v3
	v_and_b32_e32 v3, 4, v3
	s_addc_u32 s1, s1, s11
	v_or3_b32 v3, v11, v3, v10
	s_add_u32 s4, s0, 0x1000
	v_mul_u32_u24_e32 v3, 0x2e00, v3
	s_addc_u32 s5, s1, 0
	s_lshl_b32 s24, s3, 10
	v_or_b32_e32 v3, v3, v9
	s_add_i32 s64, s24, 0
	v_lshlrev_b32_e32 v11, 1, v3
	v_mov_b32_e32 v3, v1
	s_add_i32 s65, s64, 0x10000
	v_lshl_add_u64 v[2:3], s[0:1], 0, v[2:3]
	v_lshl_add_u64 v[2:3], v[2:3], 0, s[12:13]
	s_mov_b32 m0, s65
	v_mov_b32_e32 v14, v1
	global_load_lds_dwordx4 v[2:3], off
	v_add_u32_e32 v2, 0x200, v5
	v_ashrrev_i32_e32 v3, 4, v2
	v_bitop3_b32 v2, v3, v8, 7 bitop3:0x6c
	v_mul_lo_u32 v5, v3, s19
	v_lshl_or_b32 v2, v2, 4, v5
	v_and_b32_e32 v5, 0x7ffff0, v3
	v_lshrrev_b32_e32 v3, 1, v3
	v_and_b32_e32 v3, 4, v3
	v_or3_b32 v3, v5, v3, v10
	v_mul_u32_u24_e32 v3, 0x2e00, v3
	v_or_b32_e32 v3, v3, v9
	v_lshlrev_b32_e32 v5, 1, v3
	v_mov_b32_e32 v3, v1
	s_mov_b32 m0, s64
	v_lshl_add_u64 v[2:3], s[0:1], 0, v[2:3]
	global_load_lds_dwordx4 v11, s[4:5]
	v_lshl_add_u64 v[2:3], v[2:3], 0, s[12:13]
	s_add_i32 m0, s64, 0x12000
	v_mov_b32_e32 v15, v1
	global_load_lds_dwordx4 v[2:3], off
	s_add_i32 m0, s64, 0x2000
	v_mov_b32_e32 v2, v228
	global_load_lds_dwordx4 v5, s[4:5]
	s_cmp_lg_u32 0, -1
	v_and_b32_e32 v8, 0x60, v2
	v_lshlrev_b32_e32 v9, 3, v2
	v_bfe_u32 v5, v2, 2, 2
	v_and_or_b32 v8, v9, 24, v8
	v_lshrrev_b32_e32 v9, 1, v2
	v_and_b32_e32 v3, 15, v2
	v_and_or_b32 v5, v9, 8, v5
	v_ashrrev_i32_e32 v9, 4, v2
	s_cselect_b32 s24, 0, 0
	v_bitop3_b32 v10, v9, v3, 7 bitop3:0x6c
	v_mul_lo_u32 v11, v9, s19
	s_add_i32 s27, s24, 0x10000
	v_lshl_or_b32 v10, v10, 4, v11
	v_and_b32_e32 v11, 0x7ffff0, v9
	v_lshrrev_b32_e32 v9, 1, v9
	s_add_u32 s4, s0, 0x170800
	v_and_b32_e32 v9, 4, v9
	s_addc_u32 s5, s1, 0
	v_or3_b32 v9, v11, v9, v5
	s_add_u32 s0, s0, 0x171000
	v_mul_u32_u24_e32 v9, 0x2e00, v9
	s_addc_u32 s1, s1, 0
	s_add_i32 m0, s64, 0x14000
	s_add_i32 s33, s64, 0x4000
	v_or_b32_e32 v9, v9, v8
	v_add_u32_e32 v2, 0x200, v2
	v_lshlrev_b32_e32 v9, 1, v9
	global_load_lds_dwordx4 v10, s[4:5]
	s_mov_b32 m0, s33
	v_ashrrev_i32_e32 v2, 4, v2
	global_load_lds_dwordx4 v9, s[0:1]
	v_bitop3_b32 v3, v2, v3, 7 bitop3:0x6c
	v_mul_lo_u32 v9, v2, s19
	v_lshl_or_b32 v3, v3, 4, v9
	v_and_b32_e32 v9, 0x7ffff0, v2
	v_lshrrev_b32_e32 v2, 1, v2
	v_and_b32_e32 v2, 4, v2
	v_or3_b32 v2, v9, v2, v5
	v_mul_u32_u24_e32 v2, 0x2e00, v2
	v_or_b32_e32 v2, v2, v8
	s_add_i32 m0, s64, 0x16000
	v_lshlrev_b32_e32 v2, 1, v2
	global_load_lds_dwordx4 v3, s[4:5]
	s_add_i32 m0, s64, 0x6000
	v_and_b32_e32 v3, 63, v4
	global_load_lds_dwordx4 v2, s[0:1]
	v_lshlrev_b32_e32 v8, 4, v4
	v_lshlrev_b32_e32 v5, 3, v3
	v_and_b32_e32 v8, 0xc0, v8
	v_lshlrev_b32_e32 v9, 1, v4
	v_and_b32_e32 v2, 0x3fffffc0, v4
	v_and_or_b32 v8, v5, 24, v8
	v_and_b32_e32 v9, 32, v9
	v_and_b32_e32 v5, 0x100, v5
	v_lshlrev_b32_e32 v5, 3, v5
	v_bitop3_b32 v4, v7, v4, 7 bitop3:0x78
	s_cmp_gt_i32 s3, 3
	v_lshl_add_u32 v2, v2, 2, s18
	v_or3_b32 v232, v8, v9, v5
	v_lshlrev_b32_e32 v5, 8, v6
	v_lshlrev_b32_e32 v4, 4, v4
	s_cselect_b64 s[42:43], 0, 0
	s_cmp_lt_i32 s3, 4
	v_add3_u32 v233, v5, s27, v4
	s_cselect_b64 s[52:53], -1, -1
	v_cmp_gt_u32_e64 s[4:5], 32, v3
	v_lshl_add_u32 v235, v6, 2, v2
	v_add_u32_e32 v236, v2, v0
	s_add_u32 s66, s8, s7
	v_mov_b32_e32 v0, v1
	v_mov_b32_e32 v2, v1
	v_mov_b32_e32 v3, v1
	v_mov_b32_e32 v4, v1
	v_mov_b32_e32 v5, v1
	v_mov_b32_e32 v6, v1
	v_mov_b32_e32 v7, v1
	v_mov_b32_e32 v8, v1
	v_mov_b32_e32 v9, v1
	v_mov_b32_e32 v10, v1
	v_mov_b32_e32 v11, v1
	v_mov_b32_e32 v12, v1
	v_mov_b32_e32 v13, v1
	v_mov_b64_e32 v[110:111], v[14:15]
	v_mov_b64_e32 v[94:95], v[14:15]
	v_mov_b64_e32 v[46:47], v[14:15]
	v_mov_b64_e32 v[30:31], v[14:15]
	v_mov_b64_e32 v[142:143], v[14:15]
	v_mov_b64_e32 v[126:127], v[14:15]
	v_mov_b64_e32 v[78:79], v[14:15]
	v_mov_b64_e32 v[62:63], v[14:15]
	v_add_u32_e32 v234, s24, v232
	s_addc_u32 s67, s9, s6
	s_mov_b64 s[58:59], 0
	s_xor_b64 s[60:61], s[42:43], -1
	s_mov_b32 s68, 0
	v_mov_b64_e32 v[108:109], v[12:13]
	v_mov_b64_e32 v[106:107], v[10:11]
	v_mov_b64_e32 v[104:105], v[8:9]
	v_mov_b64_e32 v[102:103], v[6:7]
	v_mov_b64_e32 v[100:101], v[4:5]
	v_mov_b64_e32 v[98:99], v[2:3]
	v_mov_b64_e32 v[96:97], v[0:1]
	v_mov_b64_e32 v[92:93], v[12:13]
	v_mov_b64_e32 v[90:91], v[10:11]
	v_mov_b64_e32 v[88:89], v[8:9]
	v_mov_b64_e32 v[86:87], v[6:7]
	v_mov_b64_e32 v[84:85], v[4:5]
	v_mov_b64_e32 v[82:83], v[2:3]
	v_mov_b64_e32 v[80:81], v[0:1]
	v_mov_b64_e32 v[44:45], v[12:13]
	v_mov_b64_e32 v[42:43], v[10:11]
	v_mov_b64_e32 v[40:41], v[8:9]
	v_mov_b64_e32 v[38:39], v[6:7]
	v_mov_b64_e32 v[36:37], v[4:5]
	v_mov_b64_e32 v[34:35], v[2:3]
	v_mov_b64_e32 v[32:33], v[0:1]
	v_mov_b64_e32 v[28:29], v[12:13]
	v_mov_b64_e32 v[26:27], v[10:11]
	v_mov_b64_e32 v[24:25], v[8:9]
	v_mov_b64_e32 v[22:23], v[6:7]
	v_mov_b64_e32 v[20:21], v[4:5]
	v_mov_b64_e32 v[18:19], v[2:3]
	v_mov_b64_e32 v[16:17], v[0:1]
	v_mov_b64_e32 v[140:141], v[12:13]
	v_mov_b64_e32 v[138:139], v[10:11]
	v_mov_b64_e32 v[136:137], v[8:9]
	v_mov_b64_e32 v[134:135], v[6:7]
	v_mov_b64_e32 v[132:133], v[4:5]
	v_mov_b64_e32 v[130:131], v[2:3]
	v_mov_b64_e32 v[128:129], v[0:1]
	v_mov_b64_e32 v[124:125], v[12:13]
	v_mov_b64_e32 v[122:123], v[10:11]
	v_mov_b64_e32 v[120:121], v[8:9]
	v_mov_b64_e32 v[118:119], v[6:7]
	v_mov_b64_e32 v[116:117], v[4:5]
	v_mov_b64_e32 v[114:115], v[2:3]
	v_mov_b64_e32 v[112:113], v[0:1]
	v_mov_b64_e32 v[76:77], v[12:13]
	v_mov_b64_e32 v[74:75], v[10:11]
	v_mov_b64_e32 v[72:73], v[8:9]
	v_mov_b64_e32 v[70:71], v[6:7]
	v_mov_b64_e32 v[68:69], v[4:5]
	v_mov_b64_e32 v[66:67], v[2:3]
	v_mov_b64_e32 v[64:65], v[0:1]
	v_mov_b64_e32 v[60:61], v[12:13]
	v_mov_b64_e32 v[58:59], v[10:11]
	v_mov_b64_e32 v[56:57], v[8:9]
	v_mov_b64_e32 v[54:55], v[6:7]
	v_mov_b64_e32 v[52:53], v[4:5]
	v_mov_b64_e32 v[50:51], v[2:3]
	v_mov_b64_e32 v[48:49], v[0:1]
	s_mov_b32 s69, 0
	v_mov_b32_e32 v237, v1
	v_mov_b32_e32 v238, v1
	v_mov_b32_e32 v208, v1
	v_mov_b32_e32 v209, v1
	v_mov_b32_e32 v210, v1
	v_mov_b32_e32 v211, v1
	v_lshrrev_b32_e32 v250, 4, v228
	v_and_b32_e32 v251, 15, v228
	v_and_b32_e32 v252, 7, v250
	v_xor_b32_e32 v251, v251, v252
	v_mul_u32_u24_e32 v250, 0x5c00, v250
	v_lshl_or_b32 v250, v251, 4, v250
	v_bfe_u32 v251, v228, 2, 2
	v_bfe_u32 v252, v228, 7, 1
	v_lshl_or_b32 v251, v252, 2, v251
	v_bfe_u32 v252, v228, 4, 1
	v_lshl_or_b32 v251, v252, 3, v251
	v_bfe_u32 v252, v228, 8, 1
	v_lshl_or_b32 v251, v252, 4, v251
	v_mul_u32_u24_e32 v251, 0x5c00, v251
	v_bfe_u32 v252, v228, 5, 2
	v_lshl_or_b32 v251, v252, 6, v251
	v_and_b32_e32 v252, 3, v228
	v_lshl_or_b32 v251, v252, 4, v251
	s_waitcnt vmcnt(0)
	s_branch .LBB0_2097
